# GEMM3 stagger variant: alternate blocks within each XCD (blockIdx bit3) take the half-height unit first
# speedup vs baseline: 1.0055x; 1.0003x over previous
.Lmy_g3_cnt:
	s_add_i32 s100, s100, 1
	s_add_i32 s99, s99, s84
	s_cmp_lt_i32 s99, s55
	s_cbranch_scc1 .Lmy_g3_cnt
	s_mov_b32 s98, s100
	s_mul_i32 s101, s100, s84
	s_sub_i32 s99, s99, s84
	s_bitcmp1_b32 s75, 3
	s_cbranch_scc0 .Lmy_g3_go
	s_cmp_lt_i32 s99, s54
	s_cbranch_scc1 .Lmy_g3_go
	s_mov_b32 s75, s99
